# P4 PanelSS slot loads: 8 serialized sc1 loads batched into one wait (both exchanges)
# baseline (speedup 1.0000x reference)
.LBB0_634:
	s_waitcnt vmcnt(0) lgkmcnt(0)
	s_barrier
	v_lshl_add_u32 v199, v198, 2, 0
	s_and_saveexec_b64 s[84:85], s[8:9]
	s_cbranch_execz .LBB0_636
	v_ashrrev_i32_e32 v165, 31, v164
	s_waitcnt lgkmcnt(0)
	v_lshlrev_b64 v[166:167], 5, v[164:165]
	v_lshl_add_u64 v[166:167], s[48:49], 0, v[166:167]
	global_load_dword v214, v[166:167], off sc1
	global_load_dword v215, v[166:167], off offset:4 sc1
	global_load_dword v216, v[166:167], off offset:8 sc1
	global_load_dword v217, v[166:167], off offset:12 sc1
	global_load_dword v218, v[166:167], off offset:16 sc1
	global_load_dword v219, v[166:167], off offset:20 sc1
	global_load_dword v220, v[166:167], off offset:24 sc1
	global_load_dword v221, v[166:167], off offset:28 sc1
	s_waitcnt vmcnt(0)
	v_add_f32_e32 v155, 0, v214
	v_add_f32_e32 v155, v155, v215
	v_add_f32_e32 v155, v155, v216
	v_add_f32_e32 v155, v155, v217
	v_add_f32_e32 v155, v155, v218
	v_add_f32_e32 v155, v155, v219
	v_add_f32_e32 v155, v155, v220
	v_add_f32_e32 v155, v155, v221
	v_fmamk_f32 v155, v155, 0x3a000000, v197
	v_cmp_gt_f32_e32 vcc, s95, v155
	v_mul_f32_e32 v165, 0x4b800000, v155
	s_nop 0
	v_cndmask_b32_e32 v155, v155, v165, vcc
	v_rsq_f32_e32 v155, v155
	s_nop 0
	v_mul_f32_e32 v165, 0x45800000, v155
	v_cndmask_b32_e32 v155, v155, v165, vcc
	v_add_u32_e32 v165, 0x21200, v199
	ds_write_b32 v165, v155

.LBB0_672:
	s_waitcnt vmcnt(0) lgkmcnt(0)
	s_barrier
	s_lshl_b32 s2, s2, 8
	s_and_saveexec_b64 s[6:7], s[8:9]
	s_cbranch_execz .LBB0_674
	v_add_u32_e32 v130, s2, v198
	s_waitcnt lgkmcnt(0)
	v_ashrrev_i32_e32 v131, 31, v130
	v_lshlrev_b64 v[130:131], 5, v[130:131]
	v_lshl_add_u64 v[130:131], s[50:51], 0, v[130:131]
	global_load_dword v214, v[130:131], off sc1
	global_load_dword v215, v[130:131], off offset:4 sc1
	global_load_dword v216, v[130:131], off offset:8 sc1
	global_load_dword v217, v[130:131], off offset:12 sc1
	global_load_dword v218, v[130:131], off offset:16 sc1
	global_load_dword v219, v[130:131], off offset:20 sc1
	global_load_dword v220, v[130:131], off offset:24 sc1
	global_load_dword v221, v[130:131], off offset:28 sc1
	s_waitcnt vmcnt(0)
	v_add_f32_e32 v132, 0, v214
	v_add_f32_e32 v132, v132, v215
	v_add_f32_e32 v132, v132, v216
	v_add_f32_e32 v132, v132, v217
	v_add_f32_e32 v132, v132, v218
	v_add_f32_e32 v132, v132, v219
	v_add_f32_e32 v132, v132, v220
	v_add_f32_e32 v130, v132, v221
	v_fmamk_f32 v130, v130, 0x3a000000, v197
	v_cmp_gt_f32_e32 vcc, s95, v130
	v_mul_f32_e32 v131, 0x4b800000, v130
	s_nop 0
	v_cndmask_b32_e32 v130, v130, v131, vcc
	v_rsq_f32_e32 v130, v130
	s_nop 0
	v_mul_f32_e32 v131, 0x45800000, v130
	v_cndmask_b32_e32 v130, v130, v131, vcc
	v_add_u32_e32 v131, 0x21200, v199
	ds_write_b32 v131, v130
